# also removed s_sleep from grid-barrier poll loops
# baseline (speedup 1.0000x reference)
; __device__ __forceinline__ unsigned xb_ld(unsigned* p)              { return __hip_atomic_load(p, __ATOMIC_RELAXED, __HIP_MEMORY_SCOPE_AGENT); }
; __device__ __forceinline__ void xcd_barrier_complete(unsigned* bar, unsigned x, unsigned& nloc, unsigned& nx) {
;     const unsigned G = gridDim.x * gridDim.y * gridDim.z;
;     unsigned sum, cnt, mine, sp = 0u;
;     for (;;) {
;         sum = 0u; cnt = 0u; mine = 0u;
; #pragma unroll
;         for (unsigned j = 0; j < 16; ++j) { const unsigned c = xb_ld(&bar[XB_XCNT(j)]); sum += c; cnt += (c > 0u) ? 1u : 0u; mine = (j == x) ? c : mine; }
;         if (sum == G) break;
;         __builtin_amdgcn_s_sleep(1);
;         if ((++sp & 255u) == 0u) { if (xb_ld(&bar[XB_TMO])) break; if (sp > XB_SPIN_CAP) { atomicAdd(&bar[XB_TMO], 1u); break; } }
;     }
.LBB0_146:
	global_load_dword v15, v16, s[8:9] sc1
	global_load_dword v0, v16, s[10:11] sc1
	global_load_dword v1, v16, s[12:13] sc1
	global_load_dword v2, v16, s[14:15] sc1
	global_load_dword v3, v16, s[16:17] sc1
	global_load_dword v4, v16, s[18:19] sc1
	global_load_dword v5, v16, s[20:21] sc1
	global_load_dword v6, v16, s[22:23] sc1
	global_load_dword v7, v16, s[24:25] sc1
	global_load_dword v8, v16, s[26:27] sc1
	global_load_dword v9, v16, s[28:29] sc1
	global_load_dword v10, v16, s[30:31] sc1
	global_load_dword v11, v16, s[36:37] sc1
	global_load_dword v12, v16, s[38:39] sc1
	global_load_dword v13, v16, s[40:41] sc1
	global_load_dword v14, v16, s[42:43] sc1
	s_mov_b64 s[44:45], -1
	s_mov_b64 s[46:47], -1
	s_waitcnt vmcnt(14)
	v_add_u32_e32 v17, v0, v15
	s_waitcnt vmcnt(13)
	v_add_u32_e32 v17, v17, v1
	s_waitcnt vmcnt(12)
	v_add_u32_e32 v17, v17, v2
	s_waitcnt vmcnt(11)
	v_add_u32_e32 v17, v17, v3
	s_waitcnt vmcnt(10)
	v_add_u32_e32 v17, v17, v4
	s_waitcnt vmcnt(9)
	v_add_u32_e32 v17, v17, v5
	s_waitcnt vmcnt(8)
	v_add_u32_e32 v17, v17, v6
	s_waitcnt vmcnt(7)
	v_add_u32_e32 v17, v17, v7
	s_waitcnt vmcnt(6)
	v_add_u32_e32 v17, v17, v8
	s_waitcnt vmcnt(5)
	v_add_u32_e32 v17, v17, v9
	s_waitcnt vmcnt(4)
	v_add_u32_e32 v17, v17, v10
	s_waitcnt vmcnt(3)
	v_add_u32_e32 v17, v17, v11
	s_waitcnt vmcnt(2)
	v_add_u32_e32 v17, v17, v12
	s_waitcnt vmcnt(1)
	v_add_u32_e32 v17, v17, v13
	s_waitcnt vmcnt(0)
	v_add_u32_e32 v17, v17, v14
	v_cmp_eq_u32_e32 vcc, s0, v17
	s_cbranch_vccnz .LBB0_145
	s_and_b32 s44, s50, 0xff
	s_cmp_eq_u32 s44, 0
	s_mov_b64 s[44:45], -1
	s_mov_b64 s[48:49], -1

; __device__ __forceinline__ unsigned xb_ld(unsigned* p)              { return __hip_atomic_load(p, __ATOMIC_RELAXED, __HIP_MEMORY_SCOPE_AGENT); }
; __device__ __forceinline__ void xcd_barrier_complete(unsigned* bar, unsigned x, unsigned& nloc, unsigned& nx) {
;     ...
;         if (sum == G) break;
;         __builtin_amdgcn_s_sleep(1);
;         if ((++sp & 255u) == 0u) { if (xb_ld(&bar[XB_TMO])) break; if (sp > XB_SPIN_CAP) { atomicAdd(&bar[XB_TMO], 1u); break; } }
	s_cbranch_scc0 .LBB0_150
	global_load_dword v17, v16, s[6:7] sc1
	s_waitcnt vmcnt(0)
	v_cmp_eq_u32_e32 vcc, 0, v17
	s_cbranch_vccnz .LBB0_152
	s_mov_b64 s[48:49], 0

.LBB0_164:
	s_and_b32 s22, s0, 0xff
	s_mov_b64 s[20:21], -1
	s_cmp_lg_u32 s22, 0
	s_mov_b64 s[24:25], -1

	s_cbranch_scc1 .LBB0_167
	global_load_dword v2, v0, s[12:13] sc1
	s_waitcnt vmcnt(0)
	v_cmp_eq_u32_e32 vcc, 0, v2
	s_cbranch_vccnz .LBB0_169
	s_mov_b64 s[24:25], 0
	s_mov_b64 s[22:23], -1

.LBB0_181:
	s_and_b32 s20, s0, 0xff
	s_cmp_lg_u32 s20, 0
	s_mov_b64 s[22:23], -1

	s_cbranch_scc1 .LBB0_184
	global_load_dword v1, v0, s[12:13] sc1
	s_waitcnt vmcnt(0)
	v_cmp_eq_u32_e32 vcc, 0, v1
	s_cbranch_vccnz .LBB0_186
	s_mov_b64 s[22:23], 0
	s_mov_b64 s[20:21], -1

; __device__ __forceinline__ unsigned xb_ld(unsigned* p)              { return __hip_atomic_load(p, __ATOMIC_RELAXED, __HIP_MEMORY_SCOPE_AGENT); }
; __device__ __forceinline__ void xcd_barrier_complete(unsigned* bar, unsigned x, unsigned& nloc, unsigned& nx) {
;     const unsigned G = gridDim.x * gridDim.y * gridDim.z;
;     unsigned sum, cnt, mine, sp = 0u;
;     for (;;) {
;         sum = 0u; cnt = 0u; mine = 0u;
; #pragma unroll
;         for (unsigned j = 0; j < 16; ++j) { const unsigned c = xb_ld(&bar[XB_XCNT(j)]); sum += c; cnt += (c > 0u) ? 1u : 0u; mine = (j == x) ? c : mine; }
;         if (sum == G) break;
;         __builtin_amdgcn_s_sleep(1);
;         if ((++sp & 255u) == 0u) { if (xb_ld(&bar[XB_TMO])) break; if (sp > XB_SPIN_CAP) { atomicAdd(&bar[XB_TMO], 1u); break; } }
;     }
.LBB0_229:
	v_readlane_b32 s18, v253, 15
	v_readlane_b32 s19, v253, 16
	s_mov_b64 s[22:23], -1
	s_nop 3
	global_load_dword v0, v1, s[18:19] sc1
	v_readlane_b32 s18, v253, 17
	v_readlane_b32 s19, v253, 18
	s_nop 4
	global_load_dword v2, v1, s[18:19] sc1
	v_readlane_b32 s18, v253, 19
	v_readlane_b32 s19, v253, 20
	s_waitcnt vmcnt(0)
	v_add_u32_e32 v17, v2, v0
	s_nop 2
	global_load_dword v3, v1, s[18:19] sc1
	v_readlane_b32 s18, v253, 21
	v_readlane_b32 s19, v253, 22
	s_waitcnt vmcnt(0)
	v_add_u32_e32 v17, v17, v3
	s_nop 2
	global_load_dword v4, v1, s[18:19] sc1
	v_readlane_b32 s18, v253, 23
	v_readlane_b32 s19, v253, 24
	s_waitcnt vmcnt(0)
	v_add_u32_e32 v17, v17, v4
	s_nop 2
	global_load_dword v5, v1, s[18:19] sc1
	v_readlane_b32 s18, v253, 25
	v_readlane_b32 s19, v253, 26
	s_waitcnt vmcnt(0)
	v_add_u32_e32 v17, v17, v5
	s_nop 2
	global_load_dword v6, v1, s[18:19] sc1
	v_readlane_b32 s18, v253, 27
	v_readlane_b32 s19, v253, 28
	s_waitcnt vmcnt(0)
	v_add_u32_e32 v17, v17, v6
	s_nop 2
	global_load_dword v7, v1, s[18:19] sc1
	v_readlane_b32 s18, v253, 29
	v_readlane_b32 s19, v253, 30
	s_waitcnt vmcnt(0)
	v_add_u32_e32 v17, v17, v7
	s_nop 2
	global_load_dword v8, v1, s[18:19] sc1
	v_readlane_b32 s18, v253, 31
	v_readlane_b32 s19, v253, 32
	s_waitcnt vmcnt(0)
	v_add_u32_e32 v17, v17, v8
	s_nop 2
	global_load_dword v9, v1, s[18:19] sc1
	v_readlane_b32 s18, v253, 33
	v_readlane_b32 s19, v253, 34
	s_waitcnt vmcnt(0)
	v_add_u32_e32 v17, v17, v9
	s_nop 2
	global_load_dword v10, v1, s[18:19] sc1
	v_readlane_b32 s18, v253, 35
	v_readlane_b32 s19, v253, 36
	s_waitcnt vmcnt(0)
	v_add_u32_e32 v17, v17, v10
	s_nop 2
	global_load_dword v11, v1, s[18:19] sc1
	v_readlane_b32 s18, v253, 37
	v_readlane_b32 s19, v253, 38
	s_nop 4
	global_load_dword v12, v1, s[18:19] sc1
	global_load_dword v13, v1, s[94:95] sc1
	global_load_dword v14, v1, s[96:97] sc1
	global_load_dword v15, v1, s[64:65] sc1
	global_load_dword v16, v1, s[4:5] sc1
	s_mov_b64 s[18:19], -1
	s_waitcnt vmcnt(5)
	v_add_u32_e32 v17, v17, v11
	s_waitcnt vmcnt(4)
	v_add_u32_e32 v17, v17, v12
	s_waitcnt vmcnt(3)
	v_add_u32_e32 v17, v17, v13
	s_waitcnt vmcnt(2)
	v_add_u32_e32 v17, v17, v14
	s_waitcnt vmcnt(1)
	v_add_u32_e32 v17, v17, v15
	s_waitcnt vmcnt(0)
	v_add_u32_e32 v17, v17, v16
	v_cmp_eq_u32_e32 vcc, s40, v17
	s_cbranch_vccnz .LBB0_228
	s_and_b32 s18, s41, 0xff
	s_cmp_eq_u32 s18, 0
	s_mov_b64 s[18:19], -1
	s_mov_b64 s[34:35], -1

; __device__ __forceinline__ unsigned xb_ld(unsigned* p)              { return __hip_atomic_load(p, __ATOMIC_RELAXED, __HIP_MEMORY_SCOPE_AGENT); }
; __device__ __forceinline__ void xcd_barrier_complete(unsigned* bar, unsigned x, unsigned& nloc, unsigned& nx) {
;     ...
;         if (sum == G) break;
;         __builtin_amdgcn_s_sleep(1);
;         if ((++sp & 255u) == 0u) { if (xb_ld(&bar[XB_TMO])) break; if (sp > XB_SPIN_CAP) { atomicAdd(&bar[XB_TMO], 1u); break; } }
	s_cbranch_scc0 .LBB0_233
	global_load_dword v17, v1, s[80:81] sc1
	s_waitcnt vmcnt(0)
	v_cmp_eq_u32_e32 vcc, 0, v17
	s_cbranch_vccnz .LBB0_235
	s_mov_b64 s[34:35], 0

.LBB0_247:
	s_and_b32 s44, s48, 0xff
	s_mov_b64 s[42:43], -1
	s_cmp_lg_u32 s44, 0
	s_mov_b64 s[46:47], -1

	s_cbranch_scc1 .LBB0_250
	global_load_dword v2, v1, s[80:81] sc1
	s_waitcnt vmcnt(0)
	v_cmp_eq_u32_e32 vcc, 0, v2
	s_cbranch_vccnz .LBB0_252
	s_mov_b64 s[46:47], 0
	s_mov_b64 s[44:45], -1

; __device__ __forceinline__ unsigned xb_ld(unsigned* p)              { return __hip_atomic_load(p, __ATOMIC_RELAXED, __HIP_MEMORY_SCOPE_AGENT); }
; __device__ __forceinline__ void xcd_barrier_complete(unsigned* bar, unsigned x, unsigned& nloc, unsigned& nx) {
;     const unsigned G = gridDim.x * gridDim.y * gridDim.z;
;     unsigned sum, cnt, mine, sp = 0u;
;     for (;;) {
;         sum = 0u; cnt = 0u; mine = 0u;
; #pragma unroll
;         for (unsigned j = 0; j < 16; ++j) { const unsigned c = xb_ld(&bar[XB_XCNT(j)]); sum += c; cnt += (c > 0u) ? 1u : 0u; mine = (j == x) ? c : mine; }
;         if (sum == G) break;
;         __builtin_amdgcn_s_sleep(1);
;         if ((++sp & 255u) == 0u) { if (xb_ld(&bar[XB_TMO])) break; if (sp > XB_SPIN_CAP) { atomicAdd(&bar[XB_TMO], 1u); break; } }
;     }
.LBB0_322:
	v_readlane_b32 s18, v253, 15
	v_readlane_b32 s19, v253, 16
	s_mov_b64 s[22:23], -1
	s_nop 3
	global_load_dword v0, v1, s[18:19] sc1
	v_readlane_b32 s18, v253, 17
	v_readlane_b32 s19, v253, 18
	s_nop 4
	global_load_dword v2, v1, s[18:19] sc1
	v_readlane_b32 s18, v253, 19
	v_readlane_b32 s19, v253, 20
	s_waitcnt vmcnt(0)
	v_add_u32_e32 v17, v2, v0
	s_nop 2
	global_load_dword v3, v1, s[18:19] sc1
	v_readlane_b32 s18, v253, 21
	v_readlane_b32 s19, v253, 22
	s_waitcnt vmcnt(0)
	v_add_u32_e32 v17, v17, v3
	s_nop 2
	global_load_dword v4, v1, s[18:19] sc1
	v_readlane_b32 s18, v253, 23
	v_readlane_b32 s19, v253, 24
	s_waitcnt vmcnt(0)
	v_add_u32_e32 v17, v17, v4
	s_nop 2
	global_load_dword v5, v1, s[18:19] sc1
	v_readlane_b32 s18, v253, 25
	v_readlane_b32 s19, v253, 26
	s_waitcnt vmcnt(0)
	v_add_u32_e32 v17, v17, v5
	s_nop 2
	global_load_dword v6, v1, s[18:19] sc1
	v_readlane_b32 s18, v253, 27
	v_readlane_b32 s19, v253, 28
	s_waitcnt vmcnt(0)
	v_add_u32_e32 v17, v17, v6
	s_nop 2
	global_load_dword v7, v1, s[18:19] sc1
	v_readlane_b32 s18, v253, 29
	v_readlane_b32 s19, v253, 30
	s_waitcnt vmcnt(0)
	v_add_u32_e32 v17, v17, v7
	s_nop 2
	global_load_dword v8, v1, s[18:19] sc1
	v_readlane_b32 s18, v253, 31
	v_readlane_b32 s19, v253, 32
	s_waitcnt vmcnt(0)
	v_add_u32_e32 v17, v17, v8
	s_nop 2
	global_load_dword v9, v1, s[18:19] sc1
	v_readlane_b32 s18, v253, 33
	v_readlane_b32 s19, v253, 34
	s_waitcnt vmcnt(0)
	v_add_u32_e32 v17, v17, v9
	s_nop 2
	global_load_dword v10, v1, s[18:19] sc1
	v_readlane_b32 s18, v253, 35
	v_readlane_b32 s19, v253, 36
	s_waitcnt vmcnt(0)
	v_add_u32_e32 v17, v17, v10
	s_nop 2
	global_load_dword v11, v1, s[18:19] sc1
	v_readlane_b32 s18, v253, 37
	v_readlane_b32 s19, v253, 38
	s_nop 4
	global_load_dword v12, v1, s[18:19] sc1
	global_load_dword v13, v1, s[94:95] sc1
	global_load_dword v14, v1, s[96:97] sc1
	global_load_dword v15, v1, s[64:65] sc1
	global_load_dword v16, v1, s[4:5] sc1
	s_mov_b64 s[18:19], -1
	s_waitcnt vmcnt(5)
	v_add_u32_e32 v17, v17, v11
	s_waitcnt vmcnt(4)
	v_add_u32_e32 v17, v17, v12
	s_waitcnt vmcnt(3)
	v_add_u32_e32 v17, v17, v13
	s_waitcnt vmcnt(2)
	v_add_u32_e32 v17, v17, v14
	s_waitcnt vmcnt(1)
	v_add_u32_e32 v17, v17, v15
	s_waitcnt vmcnt(0)
	v_add_u32_e32 v17, v17, v16
	v_cmp_eq_u32_e32 vcc, s30, v17
	s_cbranch_vccnz .LBB0_321
	s_and_b32 s18, s40, 0xff
	s_cmp_eq_u32 s18, 0
	s_mov_b64 s[18:19], -1
	s_mov_b64 s[34:35], -1

; __device__ __forceinline__ unsigned xb_ld(unsigned* p)              { return __hip_atomic_load(p, __ATOMIC_RELAXED, __HIP_MEMORY_SCOPE_AGENT); }
; __device__ __forceinline__ void xcd_barrier_complete(unsigned* bar, unsigned x, unsigned& nloc, unsigned& nx) {
;     ...
;         if (sum == G) break;
;         __builtin_amdgcn_s_sleep(1);
;         if ((++sp & 255u) == 0u) { if (xb_ld(&bar[XB_TMO])) break; if (sp > XB_SPIN_CAP) { atomicAdd(&bar[XB_TMO], 1u); break; } }
	s_cbranch_scc0 .LBB0_326
	global_load_dword v17, v1, s[80:81] sc1
	s_waitcnt vmcnt(0)
	v_cmp_eq_u32_e32 vcc, 0, v17
	s_cbranch_vccnz .LBB0_328
	s_mov_b64 s[34:35], 0

.LBB0_340:
	s_and_b32 s44, s30, 0xff
	s_mov_b64 s[42:43], -1
	s_cmp_lg_u32 s44, 0
	s_mov_b64 s[46:47], -1

	s_cbranch_scc1 .LBB0_343
	global_load_dword v2, v1, s[80:81] sc1
	s_waitcnt vmcnt(0)
	v_cmp_eq_u32_e32 vcc, 0, v2
	s_cbranch_vccnz .LBB0_345
	s_mov_b64 s[46:47], 0
	s_mov_b64 s[44:45], -1

; __device__ __forceinline__ unsigned xb_ld(unsigned* p)              { return __hip_atomic_load(p, __ATOMIC_RELAXED, __HIP_MEMORY_SCOPE_AGENT); }
; __device__ __forceinline__ void xcd_barrier_complete(unsigned* bar, unsigned x, unsigned& nloc, unsigned& nx) {
;     const unsigned G = gridDim.x * gridDim.y * gridDim.z;
;     unsigned sum, cnt, mine, sp = 0u;
;     for (;;) {
;         sum = 0u; cnt = 0u; mine = 0u;
; #pragma unroll
;         for (unsigned j = 0; j < 16; ++j) { const unsigned c = xb_ld(&bar[XB_XCNT(j)]); sum += c; cnt += (c > 0u) ? 1u : 0u; mine = (j == x) ? c : mine; }
;         if (sum == G) break;
;         __builtin_amdgcn_s_sleep(1);
;         if ((++sp & 255u) == 0u) { if (xb_ld(&bar[XB_TMO])) break; if (sp > XB_SPIN_CAP) { atomicAdd(&bar[XB_TMO], 1u); break; } }
;     }
.LBB0_403:
	v_readlane_b32 s18, v253, 15
	v_readlane_b32 s19, v253, 16
	s_mov_b64 s[22:23], -1
	s_nop 3
	global_load_dword v0, v1, s[18:19] sc1
	v_readlane_b32 s18, v253, 17
	v_readlane_b32 s19, v253, 18
	s_nop 4
	global_load_dword v2, v1, s[18:19] sc1
	v_readlane_b32 s18, v253, 19
	v_readlane_b32 s19, v253, 20
	s_waitcnt vmcnt(0)
	v_add_u32_e32 v17, v2, v0
	s_nop 2
	global_load_dword v3, v1, s[18:19] sc1
	v_readlane_b32 s18, v253, 21
	v_readlane_b32 s19, v253, 22
	s_waitcnt vmcnt(0)
	v_add_u32_e32 v17, v17, v3
	s_nop 2
	global_load_dword v4, v1, s[18:19] sc1
	v_readlane_b32 s18, v253, 23
	v_readlane_b32 s19, v253, 24
	s_waitcnt vmcnt(0)
	v_add_u32_e32 v17, v17, v4
	s_nop 2
	global_load_dword v5, v1, s[18:19] sc1
	v_readlane_b32 s18, v253, 25
	v_readlane_b32 s19, v253, 26
	s_waitcnt vmcnt(0)
	v_add_u32_e32 v17, v17, v5
	s_nop 2
	global_load_dword v6, v1, s[18:19] sc1
	v_readlane_b32 s18, v253, 27
	v_readlane_b32 s19, v253, 28
	s_waitcnt vmcnt(0)
	v_add_u32_e32 v17, v17, v6
	s_nop 2
	global_load_dword v7, v1, s[18:19] sc1
	v_readlane_b32 s18, v253, 29
	v_readlane_b32 s19, v253, 30
	s_waitcnt vmcnt(0)
	v_add_u32_e32 v17, v17, v7
	s_nop 2
	global_load_dword v8, v1, s[18:19] sc1
	v_readlane_b32 s18, v253, 31
	v_readlane_b32 s19, v253, 32
	s_waitcnt vmcnt(0)
	v_add_u32_e32 v17, v17, v8
	s_nop 2
	global_load_dword v9, v1, s[18:19] sc1
	v_readlane_b32 s18, v253, 33
	v_readlane_b32 s19, v253, 34
	s_waitcnt vmcnt(0)
	v_add_u32_e32 v17, v17, v9
	s_nop 2
	global_load_dword v10, v1, s[18:19] sc1
	v_readlane_b32 s18, v253, 35
	v_readlane_b32 s19, v253, 36
	s_waitcnt vmcnt(0)
	v_add_u32_e32 v17, v17, v10
	s_nop 2
	global_load_dword v11, v1, s[18:19] sc1
	v_readlane_b32 s18, v253, 37
	v_readlane_b32 s19, v253, 38
	s_nop 4
	global_load_dword v12, v1, s[18:19] sc1
	global_load_dword v13, v1, s[94:95] sc1
	global_load_dword v14, v1, s[96:97] sc1
	global_load_dword v15, v1, s[64:65] sc1
	global_load_dword v16, v1, s[4:5] sc1
	s_mov_b64 s[18:19], -1
	s_waitcnt vmcnt(5)
	v_add_u32_e32 v17, v17, v11
	s_waitcnt vmcnt(4)
	v_add_u32_e32 v17, v17, v12
	s_waitcnt vmcnt(3)
	v_add_u32_e32 v17, v17, v13
	s_waitcnt vmcnt(2)
	v_add_u32_e32 v17, v17, v14
	s_waitcnt vmcnt(1)
	v_add_u32_e32 v17, v17, v15
	s_waitcnt vmcnt(0)
	v_add_u32_e32 v17, v17, v16
	v_cmp_eq_u32_e32 vcc, s38, v17
	s_cbranch_vccnz .LBB0_402
	s_and_b32 s18, s39, 0xff
	s_cmp_eq_u32 s18, 0
	s_mov_b64 s[18:19], -1
	s_mov_b64 s[34:35], -1

; __device__ __forceinline__ unsigned xb_ld(unsigned* p)              { return __hip_atomic_load(p, __ATOMIC_RELAXED, __HIP_MEMORY_SCOPE_AGENT); }
; __device__ __forceinline__ void xcd_barrier_complete(unsigned* bar, unsigned x, unsigned& nloc, unsigned& nx) {
;     ...
;         if (sum == G) break;
;         __builtin_amdgcn_s_sleep(1);
;         if ((++sp & 255u) == 0u) { if (xb_ld(&bar[XB_TMO])) break; if (sp > XB_SPIN_CAP) { atomicAdd(&bar[XB_TMO], 1u); break; } }
	s_cbranch_scc0 .LBB0_407
	global_load_dword v17, v1, s[80:81] sc1
	s_waitcnt vmcnt(0)
	v_cmp_eq_u32_e32 vcc, 0, v17
	s_cbranch_vccnz .LBB0_409
	s_mov_b64 s[34:35], 0

.LBB0_421:
	s_and_b32 s42, s46, 0xff
	s_mov_b64 s[40:41], -1
	s_cmp_lg_u32 s42, 0
	s_mov_b64 s[44:45], -1

	s_cbranch_scc1 .LBB0_424
	global_load_dword v2, v1, s[80:81] sc1
	s_waitcnt vmcnt(0)
	v_cmp_eq_u32_e32 vcc, 0, v2
	s_cbranch_vccnz .LBB0_426
	s_mov_b64 s[44:45], 0
	s_mov_b64 s[42:43], -1

; __device__ __forceinline__ unsigned xb_ld(unsigned* p)              { return __hip_atomic_load(p, __ATOMIC_RELAXED, __HIP_MEMORY_SCOPE_AGENT); }
; __device__ __forceinline__ void xcd_barrier_complete(unsigned* bar, unsigned x, unsigned& nloc, unsigned& nx) {
;     const unsigned G = gridDim.x * gridDim.y * gridDim.z;
;     unsigned sum, cnt, mine, sp = 0u;
;     for (;;) {
;         sum = 0u; cnt = 0u; mine = 0u;
; #pragma unroll
;         for (unsigned j = 0; j < 16; ++j) { const unsigned c = xb_ld(&bar[XB_XCNT(j)]); sum += c; cnt += (c > 0u) ? 1u : 0u; mine = (j == x) ? c : mine; }
;         if (sum == G) break;
;         __builtin_amdgcn_s_sleep(1);
;         if ((++sp & 255u) == 0u) { if (xb_ld(&bar[XB_TMO])) break; if (sp > XB_SPIN_CAP) { atomicAdd(&bar[XB_TMO], 1u); break; } }
;     }
.LBB0_484:
	v_readlane_b32 s22, v253, 15
	v_readlane_b32 s23, v253, 16
	s_mov_b64 s[34:35], -1
	s_nop 3
	global_load_dword v0, v1, s[22:23] sc1
	v_readlane_b32 s22, v253, 17
	v_readlane_b32 s23, v253, 18
	s_nop 4
	global_load_dword v2, v1, s[22:23] sc1
	v_readlane_b32 s22, v253, 19
	v_readlane_b32 s23, v253, 20
	s_waitcnt vmcnt(0)
	v_add_u32_e32 v17, v2, v0
	s_nop 2
	global_load_dword v3, v1, s[22:23] sc1
	v_readlane_b32 s22, v253, 21
	v_readlane_b32 s23, v253, 22
	s_waitcnt vmcnt(0)
	v_add_u32_e32 v17, v17, v3
	s_nop 2
	global_load_dword v4, v1, s[22:23] sc1
	v_readlane_b32 s22, v253, 23
	v_readlane_b32 s23, v253, 24
	s_waitcnt vmcnt(0)
	v_add_u32_e32 v17, v17, v4
	s_nop 2
	global_load_dword v5, v1, s[22:23] sc1
	v_readlane_b32 s22, v253, 25
	v_readlane_b32 s23, v253, 26
	s_waitcnt vmcnt(0)
	v_add_u32_e32 v17, v17, v5
	s_nop 2
	global_load_dword v6, v1, s[22:23] sc1
	v_readlane_b32 s22, v253, 27
	v_readlane_b32 s23, v253, 28
	s_waitcnt vmcnt(0)
	v_add_u32_e32 v17, v17, v6
	s_nop 2
	global_load_dword v7, v1, s[22:23] sc1
	v_readlane_b32 s22, v253, 29
	v_readlane_b32 s23, v253, 30
	s_waitcnt vmcnt(0)
	v_add_u32_e32 v17, v17, v7
	s_nop 2
	global_load_dword v8, v1, s[22:23] sc1
	v_readlane_b32 s22, v253, 31
	v_readlane_b32 s23, v253, 32
	s_waitcnt vmcnt(0)
	v_add_u32_e32 v17, v17, v8
	s_nop 2
	global_load_dword v9, v1, s[22:23] sc1
	v_readlane_b32 s22, v253, 33
	v_readlane_b32 s23, v253, 34
	s_waitcnt vmcnt(0)
	v_add_u32_e32 v17, v17, v9
	s_nop 2
	global_load_dword v10, v1, s[22:23] sc1
	v_readlane_b32 s22, v253, 35
	v_readlane_b32 s23, v253, 36
	s_waitcnt vmcnt(0)
	v_add_u32_e32 v17, v17, v10
	s_nop 2
	global_load_dword v11, v1, s[22:23] sc1
	v_readlane_b32 s22, v253, 37
	v_readlane_b32 s23, v253, 38
	s_nop 4
	global_load_dword v12, v1, s[22:23] sc1
	global_load_dword v13, v1, s[94:95] sc1
	global_load_dword v14, v1, s[96:97] sc1
	global_load_dword v15, v1, s[64:65] sc1
	global_load_dword v16, v1, s[4:5] sc1
	s_mov_b64 s[22:23], -1
	s_waitcnt vmcnt(5)
	v_add_u32_e32 v17, v17, v11
	s_waitcnt vmcnt(4)
	v_add_u32_e32 v17, v17, v12
	s_waitcnt vmcnt(3)
	v_add_u32_e32 v17, v17, v13
	s_waitcnt vmcnt(2)
	v_add_u32_e32 v17, v17, v14
	s_waitcnt vmcnt(1)
	v_add_u32_e32 v17, v17, v15
	s_waitcnt vmcnt(0)
	v_add_u32_e32 v17, v17, v16
	v_cmp_eq_u32_e32 vcc, s30, v17
	s_cbranch_vccnz .LBB0_483
	s_and_b32 s22, s40, 0xff
	s_cmp_eq_u32 s22, 0
	s_mov_b64 s[22:23], -1
	s_mov_b64 s[38:39], -1

; __device__ __forceinline__ unsigned xb_ld(unsigned* p)              { return __hip_atomic_load(p, __ATOMIC_RELAXED, __HIP_MEMORY_SCOPE_AGENT); }
; __device__ __forceinline__ void xcd_barrier_complete(unsigned* bar, unsigned x, unsigned& nloc, unsigned& nx) {
;     ...
;         if (sum == G) break;
;         __builtin_amdgcn_s_sleep(1);
;         if ((++sp & 255u) == 0u) { if (xb_ld(&bar[XB_TMO])) break; if (sp > XB_SPIN_CAP) { atomicAdd(&bar[XB_TMO], 1u); break; } }
	s_cbranch_scc0 .LBB0_488
	global_load_dword v17, v1, s[80:81] sc1
	s_waitcnt vmcnt(0)
	v_cmp_eq_u32_e32 vcc, 0, v17
	s_cbranch_vccnz .LBB0_490
	s_mov_b64 s[38:39], 0

; __device__ __forceinline__ unsigned xb_ld(unsigned* p)              { return __hip_atomic_load(p, __ATOMIC_RELAXED, __HIP_MEMORY_SCOPE_AGENT); }
; __device__ __forceinline__ void xcd_barrier_complete(unsigned* bar, unsigned x, unsigned& nloc, unsigned& nx) {
;     const unsigned G = gridDim.x * gridDim.y * gridDim.z;
;     unsigned sum, cnt, mine, sp = 0u;
;     for (;;) {
;         sum = 0u; cnt = 0u; mine = 0u;
; #pragma unroll
;         for (unsigned j = 0; j < 16; ++j) { const unsigned c = xb_ld(&bar[XB_XCNT(j)]); sum += c; cnt += (c > 0u) ? 1u : 0u; mine = (j == x) ? c : mine; }
;         if (sum == G) break;
;         __builtin_amdgcn_s_sleep(1);
;         if ((++sp & 255u) == 0u) { if (xb_ld(&bar[XB_TMO])) break; if (sp > XB_SPIN_CAP) { atomicAdd(&bar[XB_TMO], 1u); break; } }
;     }
.LBB0_657:
	v_readlane_b32 s22, v253, 15
	v_readlane_b32 s23, v253, 16
	s_mov_b64 s[34:35], -1
	s_nop 3
	global_load_dword v0, v1, s[22:23] sc1
	v_readlane_b32 s22, v253, 17
	v_readlane_b32 s23, v253, 18
	s_nop 4
	global_load_dword v2, v1, s[22:23] sc1
	v_readlane_b32 s22, v253, 19
	v_readlane_b32 s23, v253, 20
	s_waitcnt vmcnt(0)
	v_add_u32_e32 v17, v2, v0
	s_nop 2
	global_load_dword v3, v1, s[22:23] sc1
	v_readlane_b32 s22, v253, 21
	v_readlane_b32 s23, v253, 22
	s_waitcnt vmcnt(0)
	v_add_u32_e32 v17, v17, v3
	s_nop 2
	global_load_dword v4, v1, s[22:23] sc1
	v_readlane_b32 s22, v253, 23
	v_readlane_b32 s23, v253, 24
	s_waitcnt vmcnt(0)
	v_add_u32_e32 v17, v17, v4
	s_nop 2
	global_load_dword v5, v1, s[22:23] sc1
	v_readlane_b32 s22, v253, 25
	v_readlane_b32 s23, v253, 26
	s_waitcnt vmcnt(0)
	v_add_u32_e32 v17, v17, v5
	s_nop 2
	global_load_dword v6, v1, s[22:23] sc1
	v_readlane_b32 s22, v253, 27
	v_readlane_b32 s23, v253, 28
	s_waitcnt vmcnt(0)
	v_add_u32_e32 v17, v17, v6
	s_nop 2
	global_load_dword v7, v1, s[22:23] sc1
	v_readlane_b32 s22, v253, 29
	v_readlane_b32 s23, v253, 30
	s_waitcnt vmcnt(0)
	v_add_u32_e32 v17, v17, v7
	s_nop 2
	global_load_dword v8, v1, s[22:23] sc1
	v_readlane_b32 s22, v253, 31
	v_readlane_b32 s23, v253, 32
	s_waitcnt vmcnt(0)
	v_add_u32_e32 v17, v17, v8
	s_nop 2
	global_load_dword v9, v1, s[22:23] sc1
	v_readlane_b32 s22, v253, 33
	v_readlane_b32 s23, v253, 34
	s_waitcnt vmcnt(0)
	v_add_u32_e32 v17, v17, v9
	s_nop 2
	global_load_dword v10, v1, s[22:23] sc1
	v_readlane_b32 s22, v253, 35
	v_readlane_b32 s23, v253, 36
	s_waitcnt vmcnt(0)
	v_add_u32_e32 v17, v17, v10
	s_nop 2
	global_load_dword v11, v1, s[22:23] sc1
	v_readlane_b32 s22, v253, 37
	v_readlane_b32 s23, v253, 38
	s_nop 4
	global_load_dword v12, v1, s[22:23] sc1
	global_load_dword v13, v1, s[94:95] sc1
	global_load_dword v14, v1, s[96:97] sc1
	global_load_dword v15, v1, s[64:65] sc1
	global_load_dword v16, v1, s[4:5] sc1
	s_mov_b64 s[22:23], -1
	s_waitcnt vmcnt(5)
	v_add_u32_e32 v17, v17, v11
	s_waitcnt vmcnt(4)
	v_add_u32_e32 v17, v17, v12
	s_waitcnt vmcnt(3)
	v_add_u32_e32 v17, v17, v13
	s_waitcnt vmcnt(2)
	v_add_u32_e32 v17, v17, v14
	s_waitcnt vmcnt(1)
	v_add_u32_e32 v17, v17, v15
	s_waitcnt vmcnt(0)
	v_add_u32_e32 v17, v17, v16
	v_cmp_eq_u32_e32 vcc, s40, v17
	s_cbranch_vccnz .LBB0_656
	s_and_b32 s22, s41, 0xff
	s_cmp_eq_u32 s22, 0
	s_mov_b64 s[22:23], -1
	s_mov_b64 s[38:39], -1

; __device__ __forceinline__ unsigned xb_ld(unsigned* p)              { return __hip_atomic_load(p, __ATOMIC_RELAXED, __HIP_MEMORY_SCOPE_AGENT); }
; __device__ __forceinline__ void xcd_barrier_complete(unsigned* bar, unsigned x, unsigned& nloc, unsigned& nx) {
;     ...
;         if (sum == G) break;
;         __builtin_amdgcn_s_sleep(1);
;         if ((++sp & 255u) == 0u) { if (xb_ld(&bar[XB_TMO])) break; if (sp > XB_SPIN_CAP) { atomicAdd(&bar[XB_TMO], 1u); break; } }
	s_cbranch_scc0 .LBB0_661
	global_load_dword v17, v1, s[80:81] sc1
	s_waitcnt vmcnt(0)
	v_cmp_eq_u32_e32 vcc, 0, v17
	s_cbranch_vccnz .LBB0_663
	s_mov_b64 s[38:39], 0

; __device__ __forceinline__ unsigned xb_ld(unsigned* p)              { return __hip_atomic_load(p, __ATOMIC_RELAXED, __HIP_MEMORY_SCOPE_AGENT); }
; __device__ __forceinline__ void xcd_barrier_complete(unsigned* bar, unsigned x, unsigned& nloc, unsigned& nx) {
;     const unsigned G = gridDim.x * gridDim.y * gridDim.z;
;     unsigned sum, cnt, mine, sp = 0u;
;     for (;;) {
;         sum = 0u; cnt = 0u; mine = 0u;
; #pragma unroll
;         for (unsigned j = 0; j < 16; ++j) { const unsigned c = xb_ld(&bar[XB_XCNT(j)]); sum += c; cnt += (c > 0u) ? 1u : 0u; mine = (j == x) ? c : mine; }
;         if (sum == G) break;
;         __builtin_amdgcn_s_sleep(1);
;         if ((++sp & 255u) == 0u) { if (xb_ld(&bar[XB_TMO])) break; if (sp > XB_SPIN_CAP) { atomicAdd(&bar[XB_TMO], 1u); break; } }
;     }
.LBB0_786:
	v_readlane_b32 s18, v253, 15
	v_readlane_b32 s19, v253, 16
	s_mov_b64 s[22:23], -1
	s_nop 3
	global_load_dword v0, v1, s[18:19] sc1
	v_readlane_b32 s18, v253, 17
	v_readlane_b32 s19, v253, 18
	s_nop 4
	global_load_dword v2, v1, s[18:19] sc1
	v_readlane_b32 s18, v253, 19
	v_readlane_b32 s19, v253, 20
	s_waitcnt vmcnt(0)
	v_add_u32_e32 v17, v2, v0
	s_nop 2
	global_load_dword v3, v1, s[18:19] sc1
	v_readlane_b32 s18, v253, 21
	v_readlane_b32 s19, v253, 22
	s_waitcnt vmcnt(0)
	v_add_u32_e32 v17, v17, v3
	s_nop 2
	global_load_dword v4, v1, s[18:19] sc1
	v_readlane_b32 s18, v253, 23
	v_readlane_b32 s19, v253, 24
	s_waitcnt vmcnt(0)
	v_add_u32_e32 v17, v17, v4
	s_nop 2
	global_load_dword v5, v1, s[18:19] sc1
	v_readlane_b32 s18, v253, 25
	v_readlane_b32 s19, v253, 26
	s_waitcnt vmcnt(0)
	v_add_u32_e32 v17, v17, v5
	s_nop 2
	global_load_dword v6, v1, s[18:19] sc1
	v_readlane_b32 s18, v253, 27
	v_readlane_b32 s19, v253, 28
	s_waitcnt vmcnt(0)
	v_add_u32_e32 v17, v17, v6
	s_nop 2
	global_load_dword v7, v1, s[18:19] sc1
	v_readlane_b32 s18, v253, 29
	v_readlane_b32 s19, v253, 30
	s_waitcnt vmcnt(0)
	v_add_u32_e32 v17, v17, v7
	s_nop 2
	global_load_dword v8, v1, s[18:19] sc1
	v_readlane_b32 s18, v253, 31
	v_readlane_b32 s19, v253, 32
	s_waitcnt vmcnt(0)
	v_add_u32_e32 v17, v17, v8
	s_nop 2
	global_load_dword v9, v1, s[18:19] sc1
	v_readlane_b32 s18, v253, 33
	v_readlane_b32 s19, v253, 34
	s_waitcnt vmcnt(0)
	v_add_u32_e32 v17, v17, v9
	s_nop 2
	global_load_dword v10, v1, s[18:19] sc1
	v_readlane_b32 s18, v253, 35
	v_readlane_b32 s19, v253, 36
	s_waitcnt vmcnt(0)
	v_add_u32_e32 v17, v17, v10
	s_nop 2
	global_load_dword v11, v1, s[18:19] sc1
	v_readlane_b32 s18, v253, 37
	v_readlane_b32 s19, v253, 38
	s_nop 4
	global_load_dword v12, v1, s[18:19] sc1
	global_load_dword v13, v1, s[94:95] sc1
	global_load_dword v14, v1, s[96:97] sc1
	global_load_dword v15, v1, s[64:65] sc1
	global_load_dword v16, v1, s[4:5] sc1
	s_mov_b64 s[18:19], -1
	s_waitcnt vmcnt(5)
	v_add_u32_e32 v17, v17, v11
	s_waitcnt vmcnt(4)
	v_add_u32_e32 v17, v17, v12
	s_waitcnt vmcnt(3)
	v_add_u32_e32 v17, v17, v13
	s_waitcnt vmcnt(2)
	v_add_u32_e32 v17, v17, v14
	s_waitcnt vmcnt(1)
	v_add_u32_e32 v17, v17, v15
	s_waitcnt vmcnt(0)
	v_add_u32_e32 v17, v17, v16
	v_cmp_eq_u32_e32 vcc, s30, v17
	s_cbranch_vccnz .LBB0_785
	s_and_b32 s18, s38, 0xff
	s_cmp_eq_u32 s18, 0
	s_mov_b64 s[18:19], -1
	s_mov_b64 s[34:35], -1

; __device__ __forceinline__ unsigned xb_ld(unsigned* p)              { return __hip_atomic_load(p, __ATOMIC_RELAXED, __HIP_MEMORY_SCOPE_AGENT); }
; __device__ __forceinline__ void xcd_barrier_complete(unsigned* bar, unsigned x, unsigned& nloc, unsigned& nx) {
;     ...
;         if (sum == G) break;
;         __builtin_amdgcn_s_sleep(1);
;         if ((++sp & 255u) == 0u) { if (xb_ld(&bar[XB_TMO])) break; if (sp > XB_SPIN_CAP) { atomicAdd(&bar[XB_TMO], 1u); break; } }
	s_cbranch_scc0 .LBB0_790
	global_load_dword v17, v1, s[80:81] sc1
	s_waitcnt vmcnt(0)
	v_cmp_eq_u32_e32 vcc, 0, v17
	s_cbranch_vccnz .LBB0_792
	s_mov_b64 s[34:35], 0

.LBB0_804:
	s_and_b32 s42, s30, 0xff
	s_mov_b64 s[40:41], -1
	s_cmp_lg_u32 s42, 0
	s_mov_b64 s[44:45], -1

	s_cbranch_scc1 .LBB0_807
	global_load_dword v2, v1, s[80:81] sc1
	s_waitcnt vmcnt(0)
	v_cmp_eq_u32_e32 vcc, 0, v2
	s_cbranch_vccnz .LBB0_809
	s_mov_b64 s[44:45], 0
	s_mov_b64 s[42:43], -1
